# conservative variant: compiler K-loops/preambles and start grid.sync kept; only non-returning rowsq atomics, peeled C=0 first iteration, sc1 stores before global seams, post-barrier wait removal, gMLP
# baseline (speedup 1.0000x reference)
.LBB0_6:
	s_or_b64 exec, exec, s[6:7]
	v_lshrrev_b32_e32 v2, 20, v0
	v_lshrrev_b32_e32 v0, 10, v0
	v_or_b32_e32 v0, v0, v2
	s_movk_i32 s6, 0x3ff
	v_and_or_b32 v0, v0, s6, v1
	v_cmp_eq_u32_e32 vcc, 0, v0
	s_waitcnt lgkmcnt(0)
	s_barrier
	s_and_saveexec_b64 s[6:7], vcc
	s_cbranch_execz .LBB0_16
	buffer_wbl2 sc1
	s_load_dwordx2 s[4:5], s[4:5], 0x58
	v_mov_b32_e32 v2, 0
	s_mov_b64 s[10:11], exec
	v_mbcnt_lo_u32_b32 v1, s10, 0
	v_mbcnt_hi_u32_b32 v1, s11, v1
	s_waitcnt lgkmcnt(0)
	global_load_dword v0, v2, s[4:5] offset:40
	v_cmp_eq_u32_e32 vcc, 0, v1
	s_and_saveexec_b64 s[12:13], vcc
	s_cbranch_execz .LBB0_9
	s_bcnt1_i32_b64 s10, s[10:11]
	v_mov_b32_e32 v3, s10
	global_atomic_add v3, v2, v3, s[4:5] offset:32 sc0
.LBB0_9:
	s_or_b64 exec, exec, s[12:13]
	s_waitcnt vmcnt(0)
	v_readfirstlane_b32 s10, v3
	v_add_u32_e32 v2, -1, v0
	s_nop 0
	v_add_u32_e32 v1, s10, v1
	v_cmp_eq_u32_sdwa s[12:13], v1, v2 src0_sel:WORD_0 src1_sel:DWORD
	s_and_saveexec_b64 s[10:11], s[12:13]
	s_cbranch_execz .LBB0_12
	s_mov_b64 s[12:13], exec
	v_mbcnt_lo_u32_b32 v2, s12, 0
	v_mbcnt_hi_u32_b32 v2, s13, v2
	v_cmp_eq_u32_e32 vcc, 0, v2
	s_and_b64 s[14:15], exec, vcc
	s_mov_b64 exec, s[14:15]
	s_cbranch_execz .LBB0_12
	v_sub_u32_e32 v0, 0x10000, v0
	s_bcnt1_i32_b64 s12, s[12:13]
	v_mul_lo_u32 v0, v0, s12
	v_mov_b32_e32 v2, 0
	global_atomic_add v2, v0, s[4:5] offset:32
.LBB0_12:
	s_or_b64 exec, exec, s[10:11]
	v_mov_b32_e32 v0, 0
	global_load_dword v2, v0, s[4:5] offset:32 sc1
	v_and_b32_e32 v1, 0xffff0000, v1
	s_waitcnt vmcnt(0)
	v_and_b32_e32 v2, 0xffff0000, v2
	v_cmp_eq_u32_e32 vcc, v2, v1
	s_and_b64 exec, exec, vcc
	s_cbranch_execz .LBB0_15
	s_mov_b64 s[10:11], 0
.LBB0_14:
	s_sleep 1
	global_load_dword v2, v0, s[4:5] offset:32 sc1
	s_waitcnt vmcnt(0)
	v_and_b32_e32 v2, 0xffff0000, v2
	v_cmp_ne_u32_e32 vcc, v2, v1
	s_or_b64 s[10:11], vcc, s[10:11]
	s_andn2_b64 exec, exec, s[10:11]
	s_cbranch_execnz .LBB0_14
.LBB0_15:
	buffer_inv sc1
.LBB0_16:
	s_or_b64 exec, exec, s[6:7]
	s_lshr_b32 s58, s3, 6
	s_lshl_b32 s4, s2, 3
	s_add_i32 s56, s58, s4
	s_lshl_b32 s4, s58, 14
	v_mbcnt_lo_u32_b32 v0, -1, 0
	s_lshl_b32 s52, s54, 3
	s_add_i32 s33, s4, 0
	v_mbcnt_hi_u32_b32 v156, -1, v0
	s_cmpk_gt_i32 s56, 0x2a7f
	s_mov_b64 s[10:11], s[90:91]
	v_mov_b32_e32 v64, v156
	s_barrier
	s_cbranch_scc1 .LBB0_101
	s_add_i32 s4, s56, 0xffffd880
	s_and_b32 s5, s4, 0xff
	s_lshr_b32 s4, s4, 8
	s_mulk_i32 s4, 0x2780
	s_load_dwordx2 s[18:19], s[10:11], 0xc0
	s_add_i32 s4, s5, s4
	s_addk_i32 s4, 0x4880
	s_cmpk_lt_i32 s56, 0x2780
	s_cselect_b32 s26, s56, s4
	s_waitcnt lgkmcnt(0)
	s_add_u32 s42, s18, 0x300000
	s_mul_hi_i32 s4, s26, 0x67b23a55
	s_addc_u32 s43, s19, 0
	s_lshr_b32 s5, s4, 31
	s_ashr_i32 s4, s4, 12
	s_add_i32 s20, s4, s5
	s_mul_i32 s4, s20, 0x2780
	s_sub_i32 s29, s26, s4
	s_ashr_i32 s21, s20, 31
	s_mul_i32 s5, s20, 0x2980000
	s_mul_hi_i32 s4, s20, 0x2980000
	s_add_u32 s13, s42, s5
	s_addc_u32 s28, s43, s4
	s_cmpk_gt_i32 s29, 0x20ff
	s_cbranch_scc0 .LBB0_21
	s_cmpk_gt_u32 s29, 0x21ff
	s_cbranch_scc0 .LBB0_25
	s_cmpk_gt_u32 s29, 0x257f
	s_mov_b64 s[14:15], -1
	s_cbranch_scc0 .LBB0_26
	s_lshl_b32 s4, s29, 1
	s_add_i32 s4, s4, 0x7fffb500
	s_and_b32 s12, s4, 0x7fffffc0
	s_lshl_b32 s4, s29, 5
	s_and_b32 s44, s4, 0x3e0
	s_add_i32 s4, s20, -2
	s_cmpk_lt_i32 s26, 0x4f00
	s_movk_i32 s6, 0x88
	s_cselect_b32 s6, s6, 0xa8
	s_cselect_b32 s5, s21, 0
	s_cselect_b32 s4, s20, s4
	s_add_u32 s6, s10, s6
	s_addc_u32 s7, s11, 0
	s_load_dwordx2 s[6:7], s[6:7], 0x0
	s_lshl_b64 s[4:5], s[4:5], 22
	s_waitcnt lgkmcnt(0)
	s_add_u32 s6, s6, s4
	s_addc_u32 s7, s7, s5
	s_add_u32 s16, s13, 0x2780000
	s_addc_u32 s17, s28, 0
	s_mov_b64 s[4:5], 0
	s_branch .LBB0_27

.LBB0_628:
	s_ashr_i32 s13, s12, 31
	s_lshl_b64 s[6:7], s[12:13], 19
	s_add_u32 s6, s30, s6
	s_addc_u32 s7, s31, s7
	s_and_b64 s[24:25], s[38:39], exec
	s_cselect_b32 s13, s7, s35
	s_cselect_b32 s29, s6, s34
	s_ashr_i32 s5, s4, 31
	s_lshl_b64 s[24:25], s[4:5], 19
	s_add_u32 s24, s49, s24
	s_addc_u32 s25, s50, s25
	s_and_b64 s[42:43], s[38:39], exec
	s_cselect_b32 s5, s25, s41
	s_cselect_b32 s82, s24, s40
	s_add_u32 s34, s34, 0x40080
	s_addc_u32 s35, s35, 0
	s_add_u32 s83, s40, 0x100
	s_addc_u32 s84, s41, 0
	s_mov_b32 s85, -2
	s_add_u32 s40, s34, 0xfffc0080
	s_addc_u32 s41, s35, -1
	s_add_i32 s62, 0, 0x10000
	s_cmp_eq_u32 s85, 12
	s_cselect_b32 s43, s13, s41
	s_cselect_b32 s42, s29, s40
	s_cselect_b32 s41, s5, s84
	s_cselect_b32 s40, s82, s83
	s_add_i32 s63, 0, 0x14000
	v_add_u32_e32 v152, s62, v172
	v_add_u32_e32 v158, s63, v172
	ds_read_b128 v[128:131], v152
	ds_read_b128 v[144:147], v152 offset:1024
	ds_read_b128 v[148:151], v152 offset:2048
	ds_read_b128 v[152:155], v152 offset:3072
	ds_read_b128 v[174:177], v158
	ds_read_b128 v[178:181], v158 offset:1024
	ds_read_b128 v[182:185], v158 offset:2048
	ds_read_b128 v[186:189], v158 offset:3072
	v_lshl_add_u64 v[168:169], s[34:35], 0, v[140:141]
	s_add_i32 m0, s51, 0xc000
	ds_read_b128 v[190:193], v173
	ds_read_b128 v[198:201], v173 offset:1024
	ds_read_b128 v[202:205], v173 offset:2048
	ds_read_b128 v[206:209], v173 offset:3072
	ds_read_b128 v[210:213], v173 offset:4096
	ds_read_b128 v[214:217], v173 offset:5120
	ds_read_b128 v[218:221], v173 offset:6144
	ds_read_b128 v[222:225], v173 offset:7168
	global_load_lds_dwordx4 v[168:169], off
	v_lshl_add_u64 v[168:169], s[34:35], 0, v[142:143]
	s_add_i32 m0, s51, 0xe000
	s_nop 0
	global_load_lds_dwordx4 v[168:169], off
	s_waitcnt vmcnt(8)
	s_waitcnt lgkmcnt(0)
	s_barrier
	s_setprio 1
	v_mfma_f32_16x16x32_bf16 v[124:127], v[128:131], v[190:193], 0
	v_mfma_f32_16x16x32_bf16 v[116:119], v[148:151], v[190:193], 0
	v_mfma_f32_16x16x32_bf16 v[108:111], v[128:131], v[202:205], 0
	v_mfma_f32_16x16x32_bf16 v[100:103], v[148:151], v[202:205], 0
	v_mfma_f32_16x16x32_bf16 v[92:95], v[128:131], v[210:213], 0
	v_mfma_f32_16x16x32_bf16 v[84:87], v[148:151], v[210:213], 0
	v_mfma_f32_16x16x32_bf16 v[76:79], v[128:131], v[218:221], 0
	v_mfma_f32_16x16x32_bf16 v[68:71], v[148:151], v[218:221], 0
	v_mfma_f32_16x16x32_bf16 v[124:127], v[144:147], v[198:201], v[124:127]
	v_mfma_f32_16x16x32_bf16 v[116:119], v[152:155], v[198:201], v[116:119]
	v_mfma_f32_16x16x32_bf16 v[108:111], v[144:147], v[206:209], v[108:111]
	v_mfma_f32_16x16x32_bf16 v[100:103], v[152:155], v[206:209], v[100:103]
	v_mfma_f32_16x16x32_bf16 v[92:95], v[144:147], v[214:217], v[92:95]
	v_mfma_f32_16x16x32_bf16 v[84:87], v[152:155], v[214:217], v[84:87]
	v_mfma_f32_16x16x32_bf16 v[76:79], v[144:147], v[222:225], v[76:79]
	v_mfma_f32_16x16x32_bf16 v[68:71], v[152:155], v[222:225], v[68:71]
	s_setprio 0
	s_setprio 1
	v_mfma_f32_16x16x32_bf16 v[120:123], v[174:177], v[190:193], 0
	v_mfma_f32_16x16x32_bf16 v[112:115], v[182:185], v[190:193], 0
	v_mfma_f32_16x16x32_bf16 v[104:107], v[174:177], v[202:205], 0
	v_mfma_f32_16x16x32_bf16 v[96:99], v[182:185], v[202:205], 0
	v_mfma_f32_16x16x32_bf16 v[88:91], v[174:177], v[210:213], 0
	v_mfma_f32_16x16x32_bf16 v[80:83], v[182:185], v[210:213], 0
	v_mfma_f32_16x16x32_bf16 v[72:75], v[174:177], v[218:221], 0
	v_mfma_f32_16x16x32_bf16 v[64:67], v[182:185], v[218:221], 0
	v_mfma_f32_16x16x32_bf16 v[120:123], v[178:181], v[198:201], v[120:123]
	v_mfma_f32_16x16x32_bf16 v[112:115], v[186:189], v[198:201], v[112:115]
	v_mfma_f32_16x16x32_bf16 v[104:107], v[178:181], v[206:209], v[104:107]
	v_mfma_f32_16x16x32_bf16 v[96:99], v[186:189], v[206:209], v[96:99]
	v_mfma_f32_16x16x32_bf16 v[88:91], v[178:181], v[214:217], v[88:91]
	v_mfma_f32_16x16x32_bf16 v[80:83], v[186:189], v[214:217], v[80:83]
	v_mfma_f32_16x16x32_bf16 v[72:75], v[178:181], v[222:225], v[72:75]
	v_mfma_f32_16x16x32_bf16 v[64:67], v[186:189], v[222:225], v[64:67]
	s_setprio 0
	s_barrier
	s_add_i32 s62, s62, s48
	v_lshl_add_u64 v[168:169], s[40:41], 0, v[134:135]
	s_mov_b32 m0, s62
	ds_read_b128 v[190:193], v173 offset:16384
	ds_read_b128 v[198:201], v173 offset:17408
	ds_read_b128 v[202:205], v173 offset:18432
	ds_read_b128 v[206:209], v173 offset:19456
	ds_read_b128 v[210:213], v173 offset:20480
	ds_read_b128 v[214:217], v173 offset:21504
	ds_read_b128 v[218:221], v173 offset:22528
	ds_read_b128 v[222:225], v173 offset:23552
	global_load_lds_dwordx4 v[168:169], off
	s_add_i32 m0, s62, 0x2000
	s_add_u32 s86, s40, 0x40000
	v_lshl_add_u64 v[226:227], s[40:41], 0, v[138:139]
	s_addc_u32 s87, s41, 0
	s_add_i32 s62, s63, s48
	global_load_lds_dwordx4 v[226:227], off
	v_lshl_add_u64 v[228:229], s[86:87], 0, v[134:135]
	s_mov_b32 m0, s62
	v_lshl_add_u64 v[230:231], s[42:43], 0, v[136:137]
	global_load_lds_dwordx4 v[228:229], off
	v_lshl_add_u64 v[228:229], s[86:87], 0, v[138:139]
	s_add_i32 m0, s62, 0x2000
	s_nop 0
	global_load_lds_dwordx4 v[228:229], off
	v_lshl_add_u64 v[228:229], s[42:43], 0, v[132:133]
	s_mov_b32 m0, s51
	s_nop 0
	global_load_lds_dwordx4 v[228:229], off
	s_mov_b32 m0, s60
	s_nop 0
	global_load_lds_dwordx4 v[230:231], off
	s_waitcnt vmcnt(8)
	s_waitcnt lgkmcnt(0)
	s_barrier
	s_setprio 1
	v_mfma_f32_16x16x32_bf16 v[60:63], v[128:131], v[190:193], 0
	v_mfma_f32_16x16x32_bf16 v[52:55], v[148:151], v[190:193], 0
	v_mfma_f32_16x16x32_bf16 v[44:47], v[128:131], v[202:205], 0
	v_mfma_f32_16x16x32_bf16 v[36:39], v[148:151], v[202:205], 0
	v_mfma_f32_16x16x32_bf16 v[28:31], v[128:131], v[210:213], 0
	v_mfma_f32_16x16x32_bf16 v[20:23], v[148:151], v[210:213], 0
	v_mfma_f32_16x16x32_bf16 v[8:11], v[128:131], v[218:221], 0
	v_mfma_f32_16x16x32_bf16 v[4:7], v[148:151], v[218:221], 0
	v_mfma_f32_16x16x32_bf16 v[60:63], v[144:147], v[198:201], v[60:63]
	v_mfma_f32_16x16x32_bf16 v[52:55], v[152:155], v[198:201], v[52:55]
	v_mfma_f32_16x16x32_bf16 v[44:47], v[144:147], v[206:209], v[44:47]
	v_mfma_f32_16x16x32_bf16 v[36:39], v[152:155], v[206:209], v[36:39]
	v_mfma_f32_16x16x32_bf16 v[28:31], v[144:147], v[214:217], v[28:31]
	v_mfma_f32_16x16x32_bf16 v[20:23], v[152:155], v[214:217], v[20:23]
	v_mfma_f32_16x16x32_bf16 v[8:11], v[144:147], v[222:225], v[8:11]
	v_mfma_f32_16x16x32_bf16 v[4:7], v[152:155], v[222:225], v[4:7]
	s_setprio 0
	s_setprio 1
	v_mfma_f32_16x16x32_bf16 v[56:59], v[174:177], v[190:193], 0
	v_mfma_f32_16x16x32_bf16 v[48:51], v[182:185], v[190:193], 0
	v_mfma_f32_16x16x32_bf16 v[40:43], v[174:177], v[202:205], 0
	v_mfma_f32_16x16x32_bf16 v[32:35], v[182:185], v[202:205], 0
	v_mfma_f32_16x16x32_bf16 v[24:27], v[174:177], v[210:213], 0
	v_mfma_f32_16x16x32_bf16 v[16:19], v[182:185], v[210:213], 0
	v_mfma_f32_16x16x32_bf16 v[12:15], v[174:177], v[218:221], 0
	v_mfma_f32_16x16x32_bf16 v[0:3], v[182:185], v[218:221], 0
	v_mfma_f32_16x16x32_bf16 v[56:59], v[178:181], v[198:201], v[56:59]
	v_mfma_f32_16x16x32_bf16 v[48:51], v[186:189], v[198:201], v[48:51]
	v_mfma_f32_16x16x32_bf16 v[40:43], v[178:181], v[206:209], v[40:43]
	v_mfma_f32_16x16x32_bf16 v[32:35], v[186:189], v[206:209], v[32:35]
	v_mfma_f32_16x16x32_bf16 v[24:27], v[178:181], v[214:217], v[24:27]
	v_mfma_f32_16x16x32_bf16 v[16:19], v[186:189], v[214:217], v[16:19]
	v_mfma_f32_16x16x32_bf16 v[12:15], v[178:181], v[222:225], v[12:15]
	v_mfma_f32_16x16x32_bf16 v[0:3], v[186:189], v[222:225], v[0:3]
	s_setprio 0
	s_barrier
	s_add_i32 s62, 0, 0x18000
	s_add_i32 s63, 0, 0x1c000
	v_add_u32_e32 v152, s62, v172
	v_add_u32_e32 v158, s63, v172
	ds_read_b128 v[128:131], v152
	ds_read_b128 v[144:147], v152 offset:1024
	ds_read_b128 v[148:151], v152 offset:2048
	ds_read_b128 v[152:155], v152 offset:3072
	ds_read_b128 v[174:177], v158
	ds_read_b128 v[178:181], v158 offset:1024
	ds_read_b128 v[182:185], v158 offset:2048
	ds_read_b128 v[186:189], v158 offset:3072
	s_add_u32 s42, s42, 0x40000
	s_addc_u32 s43, s43, 0
	s_mov_b32 m0, s61
	v_lshl_add_u64 v[232:233], s[42:43], 0, v[132:133]
	ds_read_b128 v[190:193], v173 offset:32768
	ds_read_b128 v[198:201], v173 offset:33792
	ds_read_b128 v[202:205], v173 offset:34816
	ds_read_b128 v[206:209], v173 offset:35840
	ds_read_b128 v[210:213], v173 offset:36864
	ds_read_b128 v[214:217], v173 offset:37888
	ds_read_b128 v[218:221], v173 offset:38912
	ds_read_b128 v[222:225], v173 offset:39936
	global_load_lds_dwordx4 v[232:233], off
	v_lshl_add_u64 v[232:233], s[42:43], 0, v[136:137]
	s_mov_b32 m0, s64
	s_nop 0
	global_load_lds_dwordx4 v[232:233], off
	s_waitcnt vmcnt(8)
	s_waitcnt lgkmcnt(0)
	s_barrier
	s_setprio 1
	v_mfma_f32_16x16x32_bf16 v[124:127], v[128:131], v[190:193], v[124:127]
	v_mfma_f32_16x16x32_bf16 v[116:119], v[148:151], v[190:193], v[116:119]
	v_mfma_f32_16x16x32_bf16 v[108:111], v[128:131], v[202:205], v[108:111]
	v_mfma_f32_16x16x32_bf16 v[100:103], v[148:151], v[202:205], v[100:103]
	v_mfma_f32_16x16x32_bf16 v[92:95], v[128:131], v[210:213], v[92:95]
	v_mfma_f32_16x16x32_bf16 v[84:87], v[148:151], v[210:213], v[84:87]
	v_mfma_f32_16x16x32_bf16 v[76:79], v[128:131], v[218:221], v[76:79]
	v_mfma_f32_16x16x32_bf16 v[68:71], v[148:151], v[218:221], v[68:71]
	v_mfma_f32_16x16x32_bf16 v[124:127], v[144:147], v[198:201], v[124:127]
	v_mfma_f32_16x16x32_bf16 v[116:119], v[152:155], v[198:201], v[116:119]
	v_mfma_f32_16x16x32_bf16 v[108:111], v[144:147], v[206:209], v[108:111]
	v_mfma_f32_16x16x32_bf16 v[100:103], v[152:155], v[206:209], v[100:103]
	v_mfma_f32_16x16x32_bf16 v[92:95], v[144:147], v[214:217], v[92:95]
	v_mfma_f32_16x16x32_bf16 v[84:87], v[152:155], v[214:217], v[84:87]
	v_mfma_f32_16x16x32_bf16 v[76:79], v[144:147], v[222:225], v[76:79]
	v_mfma_f32_16x16x32_bf16 v[68:71], v[152:155], v[222:225], v[68:71]
	s_setprio 0
	s_setprio 1
	v_mfma_f32_16x16x32_bf16 v[120:123], v[174:177], v[190:193], v[120:123]
	v_mfma_f32_16x16x32_bf16 v[112:115], v[182:185], v[190:193], v[112:115]
	v_mfma_f32_16x16x32_bf16 v[104:107], v[174:177], v[202:205], v[104:107]
	v_mfma_f32_16x16x32_bf16 v[96:99], v[182:185], v[202:205], v[96:99]
	v_mfma_f32_16x16x32_bf16 v[88:91], v[174:177], v[210:213], v[88:91]
	v_mfma_f32_16x16x32_bf16 v[80:83], v[182:185], v[210:213], v[80:83]
	v_mfma_f32_16x16x32_bf16 v[72:75], v[174:177], v[218:221], v[72:75]
	v_mfma_f32_16x16x32_bf16 v[64:67], v[182:185], v[218:221], v[64:67]
	v_mfma_f32_16x16x32_bf16 v[120:123], v[178:181], v[198:201], v[120:123]
	v_mfma_f32_16x16x32_bf16 v[112:115], v[186:189], v[198:201], v[112:115]
	v_mfma_f32_16x16x32_bf16 v[104:107], v[178:181], v[206:209], v[104:107]
	v_mfma_f32_16x16x32_bf16 v[96:99], v[186:189], v[206:209], v[96:99]
	v_mfma_f32_16x16x32_bf16 v[88:91], v[178:181], v[214:217], v[88:91]
	v_mfma_f32_16x16x32_bf16 v[80:83], v[186:189], v[214:217], v[80:83]
	v_mfma_f32_16x16x32_bf16 v[72:75], v[178:181], v[222:225], v[72:75]
	v_mfma_f32_16x16x32_bf16 v[64:67], v[186:189], v[222:225], v[64:67]
	s_setprio 0
	s_barrier
	s_add_i32 s42, s62, s48
	v_lshl_add_u64 v[168:169], v[168:169], 0, s[14:15]
	s_mov_b32 m0, s42
	ds_read_b128 v[190:193], v173 offset:49152
	ds_read_b128 v[198:201], v173 offset:50176
	ds_read_b128 v[202:205], v173 offset:51200
	ds_read_b128 v[206:209], v173 offset:52224
	ds_read_b128 v[210:213], v173 offset:53248
	ds_read_b128 v[214:217], v173 offset:54272
	ds_read_b128 v[218:221], v173 offset:55296
	ds_read_b128 v[222:225], v173 offset:56320
	global_load_lds_dwordx4 v[168:169], off
	s_add_i32 m0, s42, 0x2000
	s_add_u32 s40, s40, 0x40080
	v_lshl_add_u64 v[168:169], v[226:227], 0, s[14:15]
	s_addc_u32 s41, s41, 0
	s_add_i32 s42, s63, s48
	global_load_lds_dwordx4 v[168:169], off
	v_lshl_add_u64 v[168:169], s[40:41], 0, v[134:135]
	s_mov_b32 m0, s42
	s_nop 0
	global_load_lds_dwordx4 v[168:169], off
	v_lshl_add_u64 v[168:169], s[40:41], 0, v[138:139]
	s_add_i32 m0, s42, 0x2000
	s_nop 0
	global_load_lds_dwordx4 v[168:169], off
	v_lshl_add_u64 v[168:169], v[228:229], 0, s[14:15]
	s_mov_b32 m0, s76
	s_nop 0
	global_load_lds_dwordx4 v[168:169], off
	v_lshl_add_u64 v[168:169], v[230:231], 0, s[14:15]
	s_mov_b32 m0, s77
	s_nop 0
	global_load_lds_dwordx4 v[168:169], off
	s_waitcnt vmcnt(8)
	s_waitcnt lgkmcnt(0)
	s_barrier
	s_setprio 1
	v_mfma_f32_16x16x32_bf16 v[60:63], v[128:131], v[190:193], v[60:63]
	v_mfma_f32_16x16x32_bf16 v[52:55], v[148:151], v[190:193], v[52:55]
	v_mfma_f32_16x16x32_bf16 v[44:47], v[128:131], v[202:205], v[44:47]
	v_mfma_f32_16x16x32_bf16 v[36:39], v[148:151], v[202:205], v[36:39]
	v_mfma_f32_16x16x32_bf16 v[28:31], v[128:131], v[210:213], v[28:31]
	v_mfma_f32_16x16x32_bf16 v[20:23], v[148:151], v[210:213], v[20:23]
	v_mfma_f32_16x16x32_bf16 v[8:11], v[128:131], v[218:221], v[8:11]
	v_mfma_f32_16x16x32_bf16 v[4:7], v[148:151], v[218:221], v[4:7]
	v_mfma_f32_16x16x32_bf16 v[60:63], v[144:147], v[198:201], v[60:63]
	v_mfma_f32_16x16x32_bf16 v[52:55], v[152:155], v[198:201], v[52:55]
	v_mfma_f32_16x16x32_bf16 v[44:47], v[144:147], v[206:209], v[44:47]
	v_mfma_f32_16x16x32_bf16 v[36:39], v[152:155], v[206:209], v[36:39]
	v_mfma_f32_16x16x32_bf16 v[28:31], v[144:147], v[214:217], v[28:31]
	v_mfma_f32_16x16x32_bf16 v[20:23], v[152:155], v[214:217], v[20:23]
	v_mfma_f32_16x16x32_bf16 v[8:11], v[144:147], v[222:225], v[8:11]
	v_mfma_f32_16x16x32_bf16 v[4:7], v[152:155], v[222:225], v[4:7]
	s_setprio 0
	s_setprio 1
	v_mfma_f32_16x16x32_bf16 v[56:59], v[174:177], v[190:193], v[56:59]
	v_mfma_f32_16x16x32_bf16 v[48:51], v[182:185], v[190:193], v[48:51]
	v_mfma_f32_16x16x32_bf16 v[40:43], v[174:177], v[202:205], v[40:43]
	v_mfma_f32_16x16x32_bf16 v[32:35], v[182:185], v[202:205], v[32:35]
	v_mfma_f32_16x16x32_bf16 v[24:27], v[174:177], v[210:213], v[24:27]
	v_mfma_f32_16x16x32_bf16 v[16:19], v[182:185], v[210:213], v[16:19]
	v_mfma_f32_16x16x32_bf16 v[12:15], v[174:177], v[218:221], v[12:15]
	v_mfma_f32_16x16x32_bf16 v[0:3], v[182:185], v[218:221], v[0:3]
	v_mfma_f32_16x16x32_bf16 v[56:59], v[178:181], v[198:201], v[56:59]
	v_mfma_f32_16x16x32_bf16 v[48:51], v[186:189], v[198:201], v[48:51]
	v_mfma_f32_16x16x32_bf16 v[40:43], v[178:181], v[206:209], v[40:43]
	v_mfma_f32_16x16x32_bf16 v[32:35], v[186:189], v[206:209], v[32:35]
	v_mfma_f32_16x16x32_bf16 v[24:27], v[178:181], v[214:217], v[24:27]
	v_mfma_f32_16x16x32_bf16 v[16:19], v[186:189], v[214:217], v[16:19]
	v_mfma_f32_16x16x32_bf16 v[12:15], v[178:181], v[222:225], v[12:15]
	v_mfma_f32_16x16x32_bf16 v[0:3], v[186:189], v[222:225], v[0:3]
	s_setprio 0
	s_barrier
	s_add_i32 s85, s85, 2
	s_add_u32 s34, s34, 0x100
	s_addc_u32 s35, s35, 0
	s_add_u32 s83, s83, 0x100
	s_addc_u32 s84, s84, 0
.LBB0_629:
	s_add_u32 s40, s34, 0xfffc0080
	s_addc_u32 s41, s35, -1
	s_add_i32 s62, 0, 0x10000
	s_cmp_eq_u32 s85, 12
	s_cselect_b32 s43, s13, s41
	s_cselect_b32 s42, s29, s40
	s_cselect_b32 s41, s5, s84
	s_cselect_b32 s40, s82, s83
	s_add_i32 s63, 0, 0x14000
	v_add_u32_e32 v152, s62, v172
	v_add_u32_e32 v158, s63, v172
	ds_read_b128 v[128:131], v152
	ds_read_b128 v[144:147], v152 offset:1024
	ds_read_b128 v[148:151], v152 offset:2048
	ds_read_b128 v[152:155], v152 offset:3072
	ds_read_b128 v[174:177], v158
	ds_read_b128 v[178:181], v158 offset:1024
	ds_read_b128 v[182:185], v158 offset:2048
	ds_read_b128 v[186:189], v158 offset:3072
	v_lshl_add_u64 v[168:169], s[34:35], 0, v[140:141]
	s_add_i32 m0, s51, 0xc000
	ds_read_b128 v[190:193], v173
	ds_read_b128 v[198:201], v173 offset:1024
	ds_read_b128 v[202:205], v173 offset:2048
	ds_read_b128 v[206:209], v173 offset:3072
	ds_read_b128 v[210:213], v173 offset:4096
	ds_read_b128 v[214:217], v173 offset:5120
	ds_read_b128 v[218:221], v173 offset:6144
	ds_read_b128 v[222:225], v173 offset:7168
	global_load_lds_dwordx4 v[168:169], off
	v_lshl_add_u64 v[168:169], s[34:35], 0, v[142:143]
	s_add_i32 m0, s51, 0xe000
	s_nop 0
	global_load_lds_dwordx4 v[168:169], off
	s_waitcnt vmcnt(8)
	s_waitcnt lgkmcnt(0)
	s_barrier
	s_setprio 1
	v_mfma_f32_16x16x32_bf16 v[124:127], v[128:131], v[190:193], v[124:127]
	v_mfma_f32_16x16x32_bf16 v[116:119], v[148:151], v[190:193], v[116:119]
	v_mfma_f32_16x16x32_bf16 v[108:111], v[128:131], v[202:205], v[108:111]
	v_mfma_f32_16x16x32_bf16 v[100:103], v[148:151], v[202:205], v[100:103]
	v_mfma_f32_16x16x32_bf16 v[92:95], v[128:131], v[210:213], v[92:95]
	v_mfma_f32_16x16x32_bf16 v[84:87], v[148:151], v[210:213], v[84:87]
	v_mfma_f32_16x16x32_bf16 v[76:79], v[128:131], v[218:221], v[76:79]
	v_mfma_f32_16x16x32_bf16 v[68:71], v[148:151], v[218:221], v[68:71]
	v_mfma_f32_16x16x32_bf16 v[124:127], v[144:147], v[198:201], v[124:127]
	v_mfma_f32_16x16x32_bf16 v[116:119], v[152:155], v[198:201], v[116:119]
	v_mfma_f32_16x16x32_bf16 v[108:111], v[144:147], v[206:209], v[108:111]
	v_mfma_f32_16x16x32_bf16 v[100:103], v[152:155], v[206:209], v[100:103]
	v_mfma_f32_16x16x32_bf16 v[92:95], v[144:147], v[214:217], v[92:95]
	v_mfma_f32_16x16x32_bf16 v[84:87], v[152:155], v[214:217], v[84:87]
	v_mfma_f32_16x16x32_bf16 v[76:79], v[144:147], v[222:225], v[76:79]
	v_mfma_f32_16x16x32_bf16 v[68:71], v[152:155], v[222:225], v[68:71]
	s_setprio 0
	s_setprio 1
	v_mfma_f32_16x16x32_bf16 v[120:123], v[174:177], v[190:193], v[120:123]
	v_mfma_f32_16x16x32_bf16 v[112:115], v[182:185], v[190:193], v[112:115]
	v_mfma_f32_16x16x32_bf16 v[104:107], v[174:177], v[202:205], v[104:107]
	v_mfma_f32_16x16x32_bf16 v[96:99], v[182:185], v[202:205], v[96:99]
	v_mfma_f32_16x16x32_bf16 v[88:91], v[174:177], v[210:213], v[88:91]
	v_mfma_f32_16x16x32_bf16 v[80:83], v[182:185], v[210:213], v[80:83]
	v_mfma_f32_16x16x32_bf16 v[72:75], v[174:177], v[218:221], v[72:75]
	v_mfma_f32_16x16x32_bf16 v[64:67], v[182:185], v[218:221], v[64:67]
	v_mfma_f32_16x16x32_bf16 v[120:123], v[178:181], v[198:201], v[120:123]
	v_mfma_f32_16x16x32_bf16 v[112:115], v[186:189], v[198:201], v[112:115]
	v_mfma_f32_16x16x32_bf16 v[104:107], v[178:181], v[206:209], v[104:107]
	v_mfma_f32_16x16x32_bf16 v[96:99], v[186:189], v[206:209], v[96:99]
	v_mfma_f32_16x16x32_bf16 v[88:91], v[178:181], v[214:217], v[88:91]
	v_mfma_f32_16x16x32_bf16 v[80:83], v[186:189], v[214:217], v[80:83]
	v_mfma_f32_16x16x32_bf16 v[72:75], v[178:181], v[222:225], v[72:75]
	v_mfma_f32_16x16x32_bf16 v[64:67], v[186:189], v[222:225], v[64:67]
	s_setprio 0
	s_barrier
	s_add_i32 s62, s62, s48
	v_lshl_add_u64 v[168:169], s[40:41], 0, v[134:135]
	s_mov_b32 m0, s62
	ds_read_b128 v[190:193], v173 offset:16384
	ds_read_b128 v[198:201], v173 offset:17408
	ds_read_b128 v[202:205], v173 offset:18432
	ds_read_b128 v[206:209], v173 offset:19456
	ds_read_b128 v[210:213], v173 offset:20480
	ds_read_b128 v[214:217], v173 offset:21504
	ds_read_b128 v[218:221], v173 offset:22528
	ds_read_b128 v[222:225], v173 offset:23552
	global_load_lds_dwordx4 v[168:169], off
	s_add_i32 m0, s62, 0x2000
	s_add_u32 s86, s40, 0x40000
	v_lshl_add_u64 v[226:227], s[40:41], 0, v[138:139]
	s_addc_u32 s87, s41, 0
	s_add_i32 s62, s63, s48
	global_load_lds_dwordx4 v[226:227], off
	v_lshl_add_u64 v[228:229], s[86:87], 0, v[134:135]
	s_mov_b32 m0, s62
	v_lshl_add_u64 v[230:231], s[42:43], 0, v[136:137]
	global_load_lds_dwordx4 v[228:229], off
	v_lshl_add_u64 v[228:229], s[86:87], 0, v[138:139]
	s_add_i32 m0, s62, 0x2000
	s_nop 0
	global_load_lds_dwordx4 v[228:229], off
	v_lshl_add_u64 v[228:229], s[42:43], 0, v[132:133]
	s_mov_b32 m0, s51
	s_nop 0
	global_load_lds_dwordx4 v[228:229], off
	s_mov_b32 m0, s60
	s_nop 0
	global_load_lds_dwordx4 v[230:231], off
	s_waitcnt vmcnt(8)
	s_waitcnt lgkmcnt(0)
	s_barrier
	s_setprio 1
	v_mfma_f32_16x16x32_bf16 v[60:63], v[128:131], v[190:193], v[60:63]
	v_mfma_f32_16x16x32_bf16 v[52:55], v[148:151], v[190:193], v[52:55]
	v_mfma_f32_16x16x32_bf16 v[44:47], v[128:131], v[202:205], v[44:47]
	v_mfma_f32_16x16x32_bf16 v[36:39], v[148:151], v[202:205], v[36:39]
	v_mfma_f32_16x16x32_bf16 v[28:31], v[128:131], v[210:213], v[28:31]
	v_mfma_f32_16x16x32_bf16 v[20:23], v[148:151], v[210:213], v[20:23]
	v_mfma_f32_16x16x32_bf16 v[8:11], v[128:131], v[218:221], v[8:11]
	v_mfma_f32_16x16x32_bf16 v[4:7], v[148:151], v[218:221], v[4:7]
	v_mfma_f32_16x16x32_bf16 v[60:63], v[144:147], v[198:201], v[60:63]
	v_mfma_f32_16x16x32_bf16 v[52:55], v[152:155], v[198:201], v[52:55]
	v_mfma_f32_16x16x32_bf16 v[44:47], v[144:147], v[206:209], v[44:47]
	v_mfma_f32_16x16x32_bf16 v[36:39], v[152:155], v[206:209], v[36:39]
	v_mfma_f32_16x16x32_bf16 v[28:31], v[144:147], v[214:217], v[28:31]
	v_mfma_f32_16x16x32_bf16 v[20:23], v[152:155], v[214:217], v[20:23]
	v_mfma_f32_16x16x32_bf16 v[8:11], v[144:147], v[222:225], v[8:11]
	v_mfma_f32_16x16x32_bf16 v[4:7], v[152:155], v[222:225], v[4:7]
	s_setprio 0
	s_setprio 1
	v_mfma_f32_16x16x32_bf16 v[56:59], v[174:177], v[190:193], v[56:59]
	v_mfma_f32_16x16x32_bf16 v[48:51], v[182:185], v[190:193], v[48:51]
	v_mfma_f32_16x16x32_bf16 v[40:43], v[174:177], v[202:205], v[40:43]
	v_mfma_f32_16x16x32_bf16 v[32:35], v[182:185], v[202:205], v[32:35]
	v_mfma_f32_16x16x32_bf16 v[24:27], v[174:177], v[210:213], v[24:27]
	v_mfma_f32_16x16x32_bf16 v[16:19], v[182:185], v[210:213], v[16:19]
	v_mfma_f32_16x16x32_bf16 v[12:15], v[174:177], v[218:221], v[12:15]
	v_mfma_f32_16x16x32_bf16 v[0:3], v[182:185], v[218:221], v[0:3]
	v_mfma_f32_16x16x32_bf16 v[56:59], v[178:181], v[198:201], v[56:59]
	v_mfma_f32_16x16x32_bf16 v[48:51], v[186:189], v[198:201], v[48:51]
	v_mfma_f32_16x16x32_bf16 v[40:43], v[178:181], v[206:209], v[40:43]
	v_mfma_f32_16x16x32_bf16 v[32:35], v[186:189], v[206:209], v[32:35]
	v_mfma_f32_16x16x32_bf16 v[24:27], v[178:181], v[214:217], v[24:27]
	v_mfma_f32_16x16x32_bf16 v[16:19], v[186:189], v[214:217], v[16:19]
	v_mfma_f32_16x16x32_bf16 v[12:15], v[178:181], v[222:225], v[12:15]
	v_mfma_f32_16x16x32_bf16 v[0:3], v[186:189], v[222:225], v[0:3]
	s_setprio 0
	s_barrier
	s_add_i32 s62, 0, 0x18000
	s_add_i32 s63, 0, 0x1c000
	v_add_u32_e32 v152, s62, v172
	v_add_u32_e32 v158, s63, v172
	ds_read_b128 v[128:131], v152
	ds_read_b128 v[144:147], v152 offset:1024
	ds_read_b128 v[148:151], v152 offset:2048
	ds_read_b128 v[152:155], v152 offset:3072
	ds_read_b128 v[174:177], v158
	ds_read_b128 v[178:181], v158 offset:1024
	ds_read_b128 v[182:185], v158 offset:2048
	ds_read_b128 v[186:189], v158 offset:3072
	s_add_u32 s42, s42, 0x40000
	s_addc_u32 s43, s43, 0
	s_mov_b32 m0, s61
	v_lshl_add_u64 v[232:233], s[42:43], 0, v[132:133]
	ds_read_b128 v[190:193], v173 offset:32768
	ds_read_b128 v[198:201], v173 offset:33792
	ds_read_b128 v[202:205], v173 offset:34816
	ds_read_b128 v[206:209], v173 offset:35840
	ds_read_b128 v[210:213], v173 offset:36864
	ds_read_b128 v[214:217], v173 offset:37888
	ds_read_b128 v[218:221], v173 offset:38912
	ds_read_b128 v[222:225], v173 offset:39936
	global_load_lds_dwordx4 v[232:233], off
	v_lshl_add_u64 v[232:233], s[42:43], 0, v[136:137]
	s_mov_b32 m0, s64
	s_nop 0
	global_load_lds_dwordx4 v[232:233], off
	s_waitcnt vmcnt(8)
	s_waitcnt lgkmcnt(0)
	s_barrier
	s_setprio 1
	v_mfma_f32_16x16x32_bf16 v[124:127], v[128:131], v[190:193], v[124:127]
	v_mfma_f32_16x16x32_bf16 v[116:119], v[148:151], v[190:193], v[116:119]
	v_mfma_f32_16x16x32_bf16 v[108:111], v[128:131], v[202:205], v[108:111]
	v_mfma_f32_16x16x32_bf16 v[100:103], v[148:151], v[202:205], v[100:103]
	v_mfma_f32_16x16x32_bf16 v[92:95], v[128:131], v[210:213], v[92:95]
	v_mfma_f32_16x16x32_bf16 v[84:87], v[148:151], v[210:213], v[84:87]
	v_mfma_f32_16x16x32_bf16 v[76:79], v[128:131], v[218:221], v[76:79]
	v_mfma_f32_16x16x32_bf16 v[68:71], v[148:151], v[218:221], v[68:71]
	v_mfma_f32_16x16x32_bf16 v[124:127], v[144:147], v[198:201], v[124:127]
	v_mfma_f32_16x16x32_bf16 v[116:119], v[152:155], v[198:201], v[116:119]
	v_mfma_f32_16x16x32_bf16 v[108:111], v[144:147], v[206:209], v[108:111]
	v_mfma_f32_16x16x32_bf16 v[100:103], v[152:155], v[206:209], v[100:103]
	v_mfma_f32_16x16x32_bf16 v[92:95], v[144:147], v[214:217], v[92:95]
	v_mfma_f32_16x16x32_bf16 v[84:87], v[152:155], v[214:217], v[84:87]
	v_mfma_f32_16x16x32_bf16 v[76:79], v[144:147], v[222:225], v[76:79]
	v_mfma_f32_16x16x32_bf16 v[68:71], v[152:155], v[222:225], v[68:71]
	s_setprio 0
	s_setprio 1
	v_mfma_f32_16x16x32_bf16 v[120:123], v[174:177], v[190:193], v[120:123]
	v_mfma_f32_16x16x32_bf16 v[112:115], v[182:185], v[190:193], v[112:115]
	v_mfma_f32_16x16x32_bf16 v[104:107], v[174:177], v[202:205], v[104:107]
	v_mfma_f32_16x16x32_bf16 v[96:99], v[182:185], v[202:205], v[96:99]
	v_mfma_f32_16x16x32_bf16 v[88:91], v[174:177], v[210:213], v[88:91]
	v_mfma_f32_16x16x32_bf16 v[80:83], v[182:185], v[210:213], v[80:83]
	v_mfma_f32_16x16x32_bf16 v[72:75], v[174:177], v[218:221], v[72:75]
	v_mfma_f32_16x16x32_bf16 v[64:67], v[182:185], v[218:221], v[64:67]
	v_mfma_f32_16x16x32_bf16 v[120:123], v[178:181], v[198:201], v[120:123]
	v_mfma_f32_16x16x32_bf16 v[112:115], v[186:189], v[198:201], v[112:115]
	v_mfma_f32_16x16x32_bf16 v[104:107], v[178:181], v[206:209], v[104:107]
	v_mfma_f32_16x16x32_bf16 v[96:99], v[186:189], v[206:209], v[96:99]
	v_mfma_f32_16x16x32_bf16 v[88:91], v[178:181], v[214:217], v[88:91]
	v_mfma_f32_16x16x32_bf16 v[80:83], v[186:189], v[214:217], v[80:83]
	v_mfma_f32_16x16x32_bf16 v[72:75], v[178:181], v[222:225], v[72:75]
	v_mfma_f32_16x16x32_bf16 v[64:67], v[186:189], v[222:225], v[64:67]
	s_setprio 0
	s_barrier
	s_add_i32 s42, s62, s48
	v_lshl_add_u64 v[168:169], v[168:169], 0, s[14:15]
	s_mov_b32 m0, s42
	ds_read_b128 v[190:193], v173 offset:49152
	ds_read_b128 v[198:201], v173 offset:50176
	ds_read_b128 v[202:205], v173 offset:51200
	ds_read_b128 v[206:209], v173 offset:52224
	ds_read_b128 v[210:213], v173 offset:53248
	ds_read_b128 v[214:217], v173 offset:54272
	ds_read_b128 v[218:221], v173 offset:55296
	ds_read_b128 v[222:225], v173 offset:56320
	global_load_lds_dwordx4 v[168:169], off
	s_add_i32 m0, s42, 0x2000
	s_add_u32 s40, s40, 0x40080
	v_lshl_add_u64 v[168:169], v[226:227], 0, s[14:15]
	s_addc_u32 s41, s41, 0
	s_add_i32 s42, s63, s48
	global_load_lds_dwordx4 v[168:169], off
	v_lshl_add_u64 v[168:169], s[40:41], 0, v[134:135]
	s_mov_b32 m0, s42
	s_nop 0
	global_load_lds_dwordx4 v[168:169], off
	v_lshl_add_u64 v[168:169], s[40:41], 0, v[138:139]
	s_add_i32 m0, s42, 0x2000
	s_nop 0
	global_load_lds_dwordx4 v[168:169], off
	v_lshl_add_u64 v[168:169], v[228:229], 0, s[14:15]
	s_mov_b32 m0, s76
	s_nop 0
	global_load_lds_dwordx4 v[168:169], off
	v_lshl_add_u64 v[168:169], v[230:231], 0, s[14:15]
	s_mov_b32 m0, s77
	s_nop 0
	global_load_lds_dwordx4 v[168:169], off
	s_waitcnt vmcnt(8)
	s_waitcnt lgkmcnt(0)
	s_barrier
	s_setprio 1
	v_mfma_f32_16x16x32_bf16 v[60:63], v[128:131], v[190:193], v[60:63]
	v_mfma_f32_16x16x32_bf16 v[52:55], v[148:151], v[190:193], v[52:55]
	v_mfma_f32_16x16x32_bf16 v[44:47], v[128:131], v[202:205], v[44:47]
	v_mfma_f32_16x16x32_bf16 v[36:39], v[148:151], v[202:205], v[36:39]
	v_mfma_f32_16x16x32_bf16 v[28:31], v[128:131], v[210:213], v[28:31]
	v_mfma_f32_16x16x32_bf16 v[20:23], v[148:151], v[210:213], v[20:23]
	v_mfma_f32_16x16x32_bf16 v[8:11], v[128:131], v[218:221], v[8:11]
	v_mfma_f32_16x16x32_bf16 v[4:7], v[148:151], v[218:221], v[4:7]
	v_mfma_f32_16x16x32_bf16 v[60:63], v[144:147], v[198:201], v[60:63]
	v_mfma_f32_16x16x32_bf16 v[52:55], v[152:155], v[198:201], v[52:55]
	v_mfma_f32_16x16x32_bf16 v[44:47], v[144:147], v[206:209], v[44:47]
	v_mfma_f32_16x16x32_bf16 v[36:39], v[152:155], v[206:209], v[36:39]
	v_mfma_f32_16x16x32_bf16 v[28:31], v[144:147], v[214:217], v[28:31]
	v_mfma_f32_16x16x32_bf16 v[20:23], v[152:155], v[214:217], v[20:23]
	v_mfma_f32_16x16x32_bf16 v[8:11], v[144:147], v[222:225], v[8:11]
	v_mfma_f32_16x16x32_bf16 v[4:7], v[152:155], v[222:225], v[4:7]
	s_setprio 0
	s_setprio 1
	v_mfma_f32_16x16x32_bf16 v[56:59], v[174:177], v[190:193], v[56:59]
	v_mfma_f32_16x16x32_bf16 v[48:51], v[182:185], v[190:193], v[48:51]
	v_mfma_f32_16x16x32_bf16 v[40:43], v[174:177], v[202:205], v[40:43]
	v_mfma_f32_16x16x32_bf16 v[32:35], v[182:185], v[202:205], v[32:35]
	v_mfma_f32_16x16x32_bf16 v[24:27], v[174:177], v[210:213], v[24:27]
	v_mfma_f32_16x16x32_bf16 v[16:19], v[182:185], v[210:213], v[16:19]
	v_mfma_f32_16x16x32_bf16 v[12:15], v[174:177], v[218:221], v[12:15]
	v_mfma_f32_16x16x32_bf16 v[0:3], v[182:185], v[218:221], v[0:3]
	v_mfma_f32_16x16x32_bf16 v[56:59], v[178:181], v[198:201], v[56:59]
	v_mfma_f32_16x16x32_bf16 v[48:51], v[186:189], v[198:201], v[48:51]
	v_mfma_f32_16x16x32_bf16 v[40:43], v[178:181], v[206:209], v[40:43]
	v_mfma_f32_16x16x32_bf16 v[32:35], v[186:189], v[206:209], v[32:35]
	v_mfma_f32_16x16x32_bf16 v[24:27], v[178:181], v[214:217], v[24:27]
	v_mfma_f32_16x16x32_bf16 v[16:19], v[186:189], v[214:217], v[16:19]
	v_mfma_f32_16x16x32_bf16 v[12:15], v[178:181], v[222:225], v[12:15]
	v_mfma_f32_16x16x32_bf16 v[0:3], v[186:189], v[222:225], v[0:3]
	s_setprio 0
	s_barrier
	s_add_i32 s85, s85, 2
	s_add_u32 s34, s34, 0x100
	s_addc_u32 s35, s35, 0
	s_add_u32 s83, s83, 0x100
	s_addc_u32 s84, s84, 0
	s_cmp_gt_u32 s85, 13
	s_cbranch_scc0 .LBB0_629
	s_and_b64 vcc, exec, s[2:3]
	s_cbranch_vccz .LBB0_632
	s_barrier
